# v86 + HGRN2: V^T LDS writes and next-chunk v loads moved behind the chunk-total reads at the start of step 2 (after their counted LDS waits)
# baseline (speedup 1.0000x reference)
.LBB0_1173:
	v_add_u32_e32 v242, s19, v74
	s_waitcnt vmcnt(12)
	ds_write_b16 v242, v22
	ds_write_b16_d16_hi v242, v22 offset:144
	ds_write_b16 v242, v23 offset:288
	ds_write_b16_d16_hi v242, v23 offset:432
	ds_write_b16 v242, v24 offset:576
	ds_write_b16_d16_hi v242, v24 offset:720
	ds_write_b16 v242, v25 offset:864
	ds_write_b16_d16_hi v242, v25 offset:1008
	ds_write_b16 v242, v26 offset:1152
	ds_write_b16_d16_hi v242, v26 offset:1296
	ds_write_b16 v242, v27 offset:1440
	ds_write_b16_d16_hi v242, v27 offset:1584
	ds_write_b16 v242, v28 offset:1728
	ds_write_b16_d16_hi v242, v28 offset:1872
	ds_write_b16 v242, v29 offset:2016
	ds_write_b16_d16_hi v242, v29 offset:2160
	s_mul_i32 s10, s8, 0x6000
	s_mov_b32 s11, 0
	v_lshl_add_u64 v[240:241], v[84:85], 0, s[10:11]
	global_load_dwordx4 v[22:25], v[240:241], off
	global_load_dwordx4 v[26:29], v[240:241], off offset:16
	v_readlane_b32 s6, v254, 18
	v_readlane_b32 s7, v254, 19
	s_mul_i32 s3, s20, 0x880
	s_nop 0
	v_cndmask_b32_e64 v123, v123, 0, s[6:7]
	v_cndmask_b32_e64 v122, v122, 0, s[6:7]
	v_readlane_b32 s6, v254, 26
	v_pk_add_f32 v[72:73], v[72:73], v[122:123]
	v_readlane_b32 s7, v254, 27
	s_nop 1
	v_cndmask_b32_e64 v73, v123, v73, s[6:7]
	v_cndmask_b32_e64 v72, v122, v72, s[6:7]
	v_readlane_b32 s6, v254, 28
	v_pk_add_f32 v[66:67], v[66:67], v[72:73]
	v_readlane_b32 s7, v254, 29
	s_nop 1
	v_cndmask_b32_e64 v67, v73, v67, s[6:7]
	v_cndmask_b32_e64 v66, v72, v66, s[6:7]
	v_readlane_b32 s6, v254, 30
	v_pk_add_f32 v[68:69], v[68:69], v[66:67]
	v_readlane_b32 s7, v254, 31
	s_nop 1
	v_cndmask_b32_e64 v67, v67, v69, s[6:7]
	v_cndmask_b32_e64 v66, v66, v68, s[6:7]
	v_readlane_b32 s6, v254, 32
	v_pk_add_f32 v[62:63], v[62:63], v[66:67]
	v_readlane_b32 s7, v254, 33
	v_and_b32_e32 v69, 0xffff0000, v125
	v_lshlrev_b32_e32 v68, 16, v125
	v_cndmask_b32_e64 v63, v67, v63, s[6:7]
	v_cndmask_b32_e64 v62, v66, v62, s[6:7]
	v_readlane_b32 s6, v254, 34
	v_pk_add_f32 v[64:65], v[64:65], v[62:63]
	v_readlane_b32 s7, v254, 35
	v_lshlrev_b32_e32 v66, 16, v75
	v_and_b32_e32 v67, 0xffff0000, v75
	s_mov_b32 s10, s8
	s_mul_i32 s10, s10, 0x6000
	s_mov_b32 s11, 0
	v_lshl_add_u64 v[238:239], v[78:79], 0, s[10:11]
	global_load_dword v75, v[238:239], off nt
	s_add_u32 s10, s10, 0x1000
	v_lshl_add_u64 v[240:241], v[78:79], 0, s[10:11]
	global_load_dword v125, v[240:241], off nt
	v_cndmask_b32_e64 v63, v63, v65, s[6:7]
	v_cndmask_b32_e64 v62, v62, v64, s[6:7]
	v_readlane_b32 s6, v254, 36
	v_pk_add_f32 v[58:59], v[58:59], v[62:63]
	v_readlane_b32 s7, v254, 37
	s_nop 1
	v_cndmask_b32_e64 v59, v63, v59, s[6:7]
	v_cndmask_b32_e64 v58, v62, v58, s[6:7]
	v_readlane_b32 s6, v254, 40
	v_pk_add_f32 v[60:61], v[60:61], v[58:59]
	v_readlane_b32 s7, v254, 41
	s_nop 1
	v_cndmask_b32_e64 v58, v58, v60, s[6:7]
	v_sub_f32_e32 v60, v120, v70
	v_cndmask_b32_e64 v59, v59, v61, s[6:7]
	v_exp_f32_e32 v64, v60
	v_sub_f32_e32 v60, v121, v71
	v_exp_f32_e32 v65, v60
	v_pk_add_f32 v[60:61], v[118:119], v[58:59]
	s_nop 0
	v_pk_add_f32 v[62:63], v[60:61], v[70:71] neg_lo:[0,1] neg_hi:[0,1]
	v_exp_f32_e32 v60, v60
	v_min_f32_e32 v73, 0x42e60000, v63
	v_min_f32_e64 v63, -v63, s14
	v_min_f32_e32 v72, 0x42e60000, v62
	v_min_f32_e64 v62, -v62, s14
	v_exp_f32_e32 v63, v63
	v_exp_f32_e32 v72, v72
	v_exp_f32_e32 v73, v73
	v_exp_f32_e32 v62, v62
	v_exp_f32_e32 v61, v61
	v_mul_f32_e32 v63, v63, v69
	v_add_u32_e32 v69, s3, v0
	v_mul_f32_e32 v60, v60, v66
	v_mul_f32_e32 v72, v72, v66
	v_mul_f32_e32 v73, v73, v67
	v_mul_f32_e32 v62, v62, v68
	v_cvt_pk_bf16_f32 v68, v72, v73
	ds_write_b32 v69, v68
	v_mul_f32_e32 v61, v61, v67
	v_cvt_pk_bf16_f32 v60, v60, v61
	ds_write_b32 v69, v60 offset:17408
	v_cvt_pk_bf16_f32 v60, v62, v63
	ds_write_b32 v69, v60 offset:34816
	v_pk_add_f32 v[60:61], v[116:117], v[58:59]
	v_mul_f32_e32 v66, v64, v62
	v_mul_f32_e32 v67, v63, v65
	v_pk_add_f32 v[62:63], v[60:61], v[70:71] neg_lo:[0,1] neg_hi:[0,1]
	v_exp_f32_e32 v60, v60
	v_min_f32_e32 v117, 0x42e60000, v62
	v_min_f32_e32 v118, 0x42e60000, v63
	v_min_f32_e64 v62, -v62, s14
	v_exp_f32_e32 v117, v117
	v_exp_f32_e32 v118, v118
	v_exp_f32_e32 v62, v62
	v_min_f32_e64 v63, -v63, s14
	v_exp_f32_e32 v61, v61
	v_exp_f32_e32 v63, v63
	v_lshlrev_b32_e32 v68, 16, v126
	v_and_b32_e32 v72, 0xffff0000, v126
	v_lshlrev_b32_e32 v73, 16, v127
	v_mul_f32_e32 v60, v60, v68
	v_and_b32_e32 v116, 0xffff0000, v127
	s_or_b32 s10, s8, 1
	s_mul_i32 s10, s10, 0x6000
	s_mov_b32 s11, 0
	v_lshl_add_u64 v[238:239], v[78:79], 0, s[10:11]
	global_load_dword v126, v[238:239], off nt
	s_add_u32 s10, s10, 0x1000
	v_lshl_add_u64 v[240:241], v[78:79], 0, s[10:11]
	global_load_dword v127, v[240:241], off nt
	v_mul_f32_e32 v117, v117, v68
	v_mul_f32_e32 v118, v118, v72
	v_mul_f32_e32 v62, v62, v73
	v_cvt_pk_bf16_f32 v73, v117, v118
	ds_write_b32 v69, v73 offset:272
	v_mul_f32_e32 v61, v61, v72
	v_cvt_pk_bf16_f32 v60, v60, v61
	v_mul_f32_e32 v63, v63, v116
	ds_write_b32 v69, v60 offset:17680
	v_cvt_pk_bf16_f32 v60, v62, v63
	ds_write_b32 v69, v60 offset:35088
	v_pk_add_f32 v[60:61], v[114:115], v[58:59]
	v_mul_f32_e32 v68, v64, v62
	v_mul_f32_e32 v72, v63, v65
	v_pk_add_f32 v[62:63], v[60:61], v[70:71] neg_lo:[0,1] neg_hi:[0,1]
	v_exp_f32_e32 v60, v60
	v_min_f32_e32 v117, 0x42e60000, v62
	v_min_f32_e32 v118, 0x42e60000, v63
	v_min_f32_e64 v62, -v62, s14
	v_exp_f32_e32 v117, v117
	v_exp_f32_e32 v118, v118
	v_exp_f32_e32 v62, v62
	v_min_f32_e64 v63, -v63, s14
	v_exp_f32_e32 v61, v61
	v_exp_f32_e32 v63, v63
	v_lshlrev_b32_e32 v73, 16, v128
	v_and_b32_e32 v114, 0xffff0000, v128
	v_lshlrev_b32_e32 v115, 16, v129
	v_mul_f32_e32 v60, v60, v73
	v_and_b32_e32 v116, 0xffff0000, v129
	s_or_b32 s10, s8, 2
	s_mul_i32 s10, s10, 0x6000
	s_mov_b32 s11, 0
	v_lshl_add_u64 v[238:239], v[78:79], 0, s[10:11]
	global_load_dword v128, v[238:239], off nt
	s_add_u32 s10, s10, 0x1000
	v_lshl_add_u64 v[240:241], v[78:79], 0, s[10:11]
	global_load_dword v129, v[240:241], off nt
	v_mul_f32_e32 v117, v117, v73
	v_mul_f32_e32 v118, v118, v114
	v_mul_f32_e32 v62, v62, v115
	v_cvt_pk_bf16_f32 v115, v117, v118
	ds_write_b32 v69, v115 offset:544
	v_mul_f32_e32 v61, v61, v114
	v_cvt_pk_bf16_f32 v60, v60, v61
	v_mul_f32_e32 v63, v63, v116
	ds_write_b32 v69, v60 offset:17952
	v_cvt_pk_bf16_f32 v60, v62, v63
	ds_write_b32 v69, v60 offset:35360
	v_pk_add_f32 v[60:61], v[112:113], v[58:59]
	v_mul_f32_e32 v73, v64, v62
	v_mul_f32_e32 v114, v63, v65
	v_pk_add_f32 v[62:63], v[60:61], v[70:71] neg_lo:[0,1] neg_hi:[0,1]
	v_exp_f32_e32 v60, v60
	v_min_f32_e32 v117, 0x42e60000, v62
	v_min_f32_e32 v118, 0x42e60000, v63
	v_min_f32_e64 v62, -v62, s14
	v_exp_f32_e32 v117, v117
	v_exp_f32_e32 v118, v118
	v_exp_f32_e32 v62, v62
	v_min_f32_e64 v63, -v63, s14
	v_exp_f32_e32 v61, v61
	v_exp_f32_e32 v63, v63
	v_lshlrev_b32_e32 v112, 16, v130
	v_and_b32_e32 v113, 0xffff0000, v130
	v_lshlrev_b32_e32 v115, 16, v131
	v_mul_f32_e32 v60, v60, v112
	v_and_b32_e32 v116, 0xffff0000, v131
	s_or_b32 s10, s8, 3
	s_mul_i32 s10, s10, 0x6000
	s_mov_b32 s11, 0
	v_lshl_add_u64 v[238:239], v[78:79], 0, s[10:11]
	global_load_dword v130, v[238:239], off nt
	s_add_u32 s10, s10, 0x1000
	v_lshl_add_u64 v[240:241], v[78:79], 0, s[10:11]
	global_load_dword v131, v[240:241], off nt
	v_mul_f32_e32 v117, v117, v112
	v_mul_f32_e32 v118, v118, v113
	v_mul_f32_e32 v62, v62, v115
	v_cvt_pk_bf16_f32 v115, v117, v118
	ds_write_b32 v69, v115 offset:816
	v_mul_f32_e32 v61, v61, v113
	v_cvt_pk_bf16_f32 v60, v60, v61
	v_mul_f32_e32 v63, v63, v116
	ds_write_b32 v69, v60 offset:18224
	v_cvt_pk_bf16_f32 v60, v62, v63
	ds_write_b32 v69, v60 offset:35632
	v_pk_add_f32 v[60:61], v[110:111], v[58:59]
	v_mul_f32_e32 v112, v64, v62
	v_mul_f32_e32 v113, v63, v65
	v_pk_add_f32 v[62:63], v[60:61], v[70:71] neg_lo:[0,1] neg_hi:[0,1]
	v_exp_f32_e32 v60, v60
	v_min_f32_e32 v117, 0x42e60000, v62
	v_min_f32_e32 v118, 0x42e60000, v63
	v_min_f32_e64 v62, -v62, s14
	v_exp_f32_e32 v117, v117
	v_exp_f32_e32 v118, v118
	v_exp_f32_e32 v62, v62
	v_min_f32_e64 v63, -v63, s14
	v_exp_f32_e32 v61, v61
	v_exp_f32_e32 v63, v63
	v_lshlrev_b32_e32 v110, 16, v140
	v_and_b32_e32 v111, 0xffff0000, v140
	v_lshlrev_b32_e32 v115, 16, v142
	v_mul_f32_e32 v60, v60, v110
	v_and_b32_e32 v116, 0xffff0000, v142
	s_or_b32 s10, s8, 4
	s_mul_i32 s10, s10, 0x6000
	s_mov_b32 s11, 0
	v_lshl_add_u64 v[238:239], v[78:79], 0, s[10:11]
	global_load_dword v140, v[238:239], off nt
	s_add_u32 s10, s10, 0x1000
	v_lshl_add_u64 v[240:241], v[78:79], 0, s[10:11]
	global_load_dword v142, v[240:241], off nt
	v_mul_f32_e32 v117, v117, v110
	v_mul_f32_e32 v118, v118, v111
	v_mul_f32_e32 v62, v62, v115
	v_cvt_pk_bf16_f32 v115, v117, v118
	ds_write_b32 v69, v115 offset:1088
	v_mul_f32_e32 v61, v61, v111
	v_cvt_pk_bf16_f32 v60, v60, v61
	v_mul_f32_e32 v63, v63, v116
	ds_write_b32 v69, v60 offset:18496
	v_cvt_pk_bf16_f32 v60, v62, v63
	ds_write_b32 v69, v60 offset:35904
	v_pk_add_f32 v[60:61], v[108:109], v[58:59]
	v_mul_f32_e32 v110, v64, v62
	v_mul_f32_e32 v111, v63, v65
	v_pk_add_f32 v[62:63], v[60:61], v[70:71] neg_lo:[0,1] neg_hi:[0,1]
	v_exp_f32_e32 v60, v60
	v_min_f32_e32 v117, 0x42e60000, v62
	v_min_f32_e32 v118, 0x42e60000, v63
	v_min_f32_e64 v62, -v62, s14
	v_exp_f32_e32 v117, v117
	v_exp_f32_e32 v118, v118
	v_exp_f32_e32 v62, v62
	v_min_f32_e64 v63, -v63, s14
	v_exp_f32_e32 v61, v61
	v_exp_f32_e32 v63, v63
	v_lshlrev_b32_e32 v108, 16, v144
	v_and_b32_e32 v109, 0xffff0000, v144
	v_lshlrev_b32_e32 v115, 16, v149
	v_mul_f32_e32 v60, v60, v108
	v_and_b32_e32 v116, 0xffff0000, v149
	s_or_b32 s10, s8, 5
	s_mul_i32 s10, s10, 0x6000
	s_mov_b32 s11, 0
	v_lshl_add_u64 v[238:239], v[78:79], 0, s[10:11]
	global_load_dword v144, v[238:239], off nt
	s_add_u32 s10, s10, 0x1000
	v_lshl_add_u64 v[240:241], v[78:79], 0, s[10:11]
	global_load_dword v149, v[240:241], off nt
	v_mul_f32_e32 v117, v117, v108
	v_mul_f32_e32 v118, v118, v109
	v_mul_f32_e32 v62, v62, v115
	v_cvt_pk_bf16_f32 v115, v117, v118
	ds_write_b32 v69, v115 offset:1360
	v_mul_f32_e32 v61, v61, v109
	v_cvt_pk_bf16_f32 v60, v60, v61
	v_mul_f32_e32 v63, v63, v116
	ds_write_b32 v69, v60 offset:18768
	v_cvt_pk_bf16_f32 v60, v62, v63
	ds_write_b32 v69, v60 offset:36176
	v_pk_add_f32 v[60:61], v[106:107], v[58:59]
	v_mul_f32_e32 v108, v64, v62
	v_mul_f32_e32 v109, v63, v65
	v_pk_add_f32 v[62:63], v[60:61], v[70:71] neg_lo:[0,1] neg_hi:[0,1]
	v_exp_f32_e32 v60, v60
	v_min_f32_e32 v117, 0x42e60000, v62
	v_min_f32_e32 v118, 0x42e60000, v63
	v_min_f32_e64 v62, -v62, s14
	v_exp_f32_e32 v117, v117
	v_exp_f32_e32 v118, v118
	v_exp_f32_e32 v62, v62
	v_min_f32_e64 v63, -v63, s14
	v_exp_f32_e32 v61, v61
	v_exp_f32_e32 v63, v63
	v_lshlrev_b32_e32 v106, 16, v156
	v_and_b32_e32 v107, 0xffff0000, v156
	v_lshlrev_b32_e32 v115, 16, v157
	v_mul_f32_e32 v60, v60, v106
	v_and_b32_e32 v116, 0xffff0000, v157
	s_or_b32 s10, s8, 6
	s_mul_i32 s10, s10, 0x6000
	s_mov_b32 s11, 0
	v_lshl_add_u64 v[238:239], v[78:79], 0, s[10:11]
	global_load_dword v156, v[238:239], off nt
	s_add_u32 s10, s10, 0x1000
	v_lshl_add_u64 v[240:241], v[78:79], 0, s[10:11]
	global_load_dword v157, v[240:241], off nt
	v_mul_f32_e32 v117, v117, v106
	v_mul_f32_e32 v118, v118, v107
	v_mul_f32_e32 v62, v62, v115
	v_cvt_pk_bf16_f32 v115, v117, v118
	ds_write_b32 v69, v115 offset:1632
	v_mul_f32_e32 v61, v61, v107
	v_cvt_pk_bf16_f32 v60, v60, v61
	v_mul_f32_e32 v63, v63, v116
	ds_write_b32 v69, v60 offset:19040
	v_cvt_pk_bf16_f32 v60, v62, v63
	v_pk_add_f32 v[58:59], v[104:105], v[58:59]
	ds_write_b32 v69, v60 offset:36448
	v_pk_add_f32 v[60:61], v[58:59], v[70:71] neg_lo:[0,1] neg_hi:[0,1]
	v_exp_f32_e32 v58, v58
	v_min_f32_e32 v106, 0x42e60000, v60
	v_min_f32_e32 v107, 0x42e60000, v61
	v_min_f32_e64 v60, -v60, s14
	v_exp_f32_e32 v106, v106
	v_exp_f32_e32 v107, v107
	v_exp_f32_e32 v60, v60
	v_min_f32_e64 v61, -v61, s14
	v_exp_f32_e32 v59, v59
	v_exp_f32_e32 v61, v61
	v_lshlrev_b32_e32 v70, 16, v158
	v_and_b32_e32 v71, 0xffff0000, v158
	v_lshlrev_b32_e32 v104, 16, v159
	v_mul_f32_e32 v58, v58, v70
	v_and_b32_e32 v105, 0xffff0000, v159
	s_or_b32 s10, s8, 7
	s_mul_i32 s10, s10, 0x6000
	s_mov_b32 s11, 0
	v_lshl_add_u64 v[238:239], v[78:79], 0, s[10:11]
	global_load_dword v158, v[238:239], off nt
	s_add_u32 s10, s10, 0x1000
	v_lshl_add_u64 v[240:241], v[78:79], 0, s[10:11]
	global_load_dword v159, v[240:241], off nt
	v_mul_f32_e32 v106, v106, v70
	v_mul_f32_e32 v107, v107, v71
	v_mul_f32_e32 v60, v60, v104
	v_cvt_pk_bf16_f32 v104, v106, v107
	ds_write_b32 v69, v104 offset:1904
	v_mul_f32_e32 v59, v59, v71
	v_cvt_pk_bf16_f32 v58, v58, v59
	v_mul_f32_e32 v61, v61, v105
	ds_write_b32 v69, v58 offset:19312
	v_cvt_pk_bf16_f32 v58, v60, v61
	ds_write_b32 v69, v58 offset:36720
	v_cvt_pk_bf16_f32 v58, v66, v68
	v_mul_f32_e32 v62, v64, v62
	v_mul_f32_e32 v63, v63, v65
	v_mul_f32_e32 v64, v64, v60
	v_mul_f32_e32 v65, v61, v65
	v_cvt_pk_bf16_f32 v59, v73, v112
	v_cvt_pk_bf16_f32 v60, v110, v108
	v_cvt_pk_bf16_f32 v61, v62, v64
	ds_write_b128 v143, v[58:61] offset:52224
	v_cvt_pk_bf16_f32 v58, v67, v72
	s_add_i32 s3, s2, 1
	v_cvt_pk_bf16_f32 v59, v114, v113
	v_cvt_pk_bf16_f32 v60, v111, v109
	v_cvt_pk_bf16_f32 v61, v63, v65
	ds_write_b128 v143, v[58:61] offset:52368
